# attn0 plain loop: softmax denominator accumulated per half-wave, rescale factor applied to it only on the rare path, halves combined at loop exit
# baseline (speedup 1.0000x reference)
.LBB0_309:
	s_mov_b32 s77, s74
	v_add3_u32 v215, s77, v209, v208
	v_add3_u32 v216, s77, v210, v208
	v_add3_u32 v233, s77, v211, v208
	v_add3_u32 v254, s77, v212, v208
	ds_read_b128 v[234:237], v215 offset:49152
	ds_read_b128 v[238:241], v215 offset:57344
	ds_read_b128 v[242:245], v216 offset:49152
	ds_read_b128 v[246:249], v216 offset:57344
	ds_read_b128 v[250:253], v233 offset:49152
	s_add_u32 s4, s70, 0xffffc000
	s_mov_b32 s74, s72
	s_addc_u32 s5, s71, -1
	s_add_i32 s72, s72, s42
	s_setprio 1
	s_waitcnt lgkmcnt(4)
	v_mfma_f32_32x32x16_bf16 v[112:127], v[234:237], v[188:191], 0
	ds_read_b128 v[234:237], v233 offset:57344
	v_add_f32_e32 v1, 0, v230
	v_add_f32_e32 v1, v232, v1
	v_add_f32_e32 v1, v228, v1
	v_add_f32_e32 v1, v231, v1
	v_add_f32_e32 v1, v226, v1
	s_waitcnt lgkmcnt(4)
	v_mfma_f32_32x32x16_bf16 v[96:111], v[238:241], v[188:191], 0
	ds_read_b128 v[238:241], v254 offset:49152
	v_add_f32_e32 v1, v229, v1
	v_add_f32_e32 v1, v225, v1
	v_add_f32_e32 v1, v227, v1
	v_add_f32_e32 v1, v222, v1
	v_add_f32_e32 v1, v224, v1
	s_waitcnt lgkmcnt(4)
	v_mfma_f32_32x32x16_bf16 v[112:127], v[242:245], v[184:187], v[112:127]
	ds_read_b128 v[242:245], v254 offset:57344
	s_mov_b32 s73, m0
	s_mov_b32 m0, s72
	s_nop 0
	global_load_lds_dwordx4 v197, s[4:5]
	s_mov_b32 m0, s73
	v_add_f32_e32 v1, v220, v1
	v_add_f32_e32 v1, v223, v1
	v_exp_f32_e32 v2, v128
	v_add_f32_e32 v1, v218, v1
	s_waitcnt lgkmcnt(4)
	v_mfma_f32_32x32x16_bf16 v[96:111], v[246:249], v[184:187], v[96:111]
	ds_read_b128 v[246:249], v215 offset:49280
	v_exp_f32_e32 v12, v129
	v_add_f32_e32 v1, v221, v1
	v_exp_f32_e32 v13, v130
	s_waitcnt lgkmcnt(4)
	v_mfma_f32_32x32x16_bf16 v[112:127], v[250:253], v[180:183], v[112:127]
	ds_read_b128 v[250:253], v215 offset:57472
	v_add_f32_e32 v1, v217, v1
	v_exp_f32_e32 v14, v131
	v_add_f32_e32 v1, v219, v1
	v_exp_f32_e32 v15, v132
	s_waitcnt lgkmcnt(4)
	v_mfma_f32_32x32x16_bf16 v[96:111], v[234:237], v[180:183], v[96:111]
	ds_read_b128 v[234:237], v216 offset:49280
	s_addk_i32 s72, 0x400
	s_mov_b32 s73, m0
	s_mov_b32 m0, s72
	s_nop 0
	global_load_lds_dwordx4 v198, s[4:5]
	s_mov_b32 m0, s73
	v_add_f32_e32 v1, v2, v1
	v_exp_f32_e32 v18, v133
	v_add_f32_e32 v1, v12, v1
	s_waitcnt lgkmcnt(4)
	v_mfma_f32_32x32x16_bf16 v[112:127], v[238:241], v[176:179], v[112:127]
	ds_read_b128 v[238:241], v216 offset:57472
	v_exp_f32_e32 v19, v134
	v_add_f32_e32 v1, v13, v1
	v_exp_f32_e32 v20, v135
	v_add_f32_e32 v1, v14, v1
	s_waitcnt lgkmcnt(4)
	v_mfma_f32_32x32x16_bf16 v[96:111], v[242:245], v[176:179], v[96:111]
	ds_read_b128 v[242:245], v233 offset:49280
	v_exp_f32_e32 v21, v136
	v_add_f32_e32 v1, v15, v1
	v_exp_f32_e32 v22, v137
	s_waitcnt lgkmcnt(4)
	v_mfma_f32_32x32x16_bf16 v[112:127], v[246:249], v[172:175], v[112:127]
	ds_read_b128 v[246:249], v233 offset:57472
	s_add_i32 s4, s69, s97
	s_mov_b32 s5, m0
	s_mov_b32 m0, s4
	s_nop 0
	global_load_lds_dwordx4 v199, s[56:57]
	s_mov_b32 m0, s5
	v_add_f32_e32 v1, v18, v1
	v_exp_f32_e32 v23, v138
	v_add_f32_e32 v1, v19, v1
	s_waitcnt lgkmcnt(4)
	v_mfma_f32_32x32x16_bf16 v[96:111], v[250:253], v[172:175], v[96:111]
	ds_read_b128 v[250:253], v254 offset:49280
	v_exp_f32_e32 v24, v139
	v_add_f32_e32 v1, v20, v1
	v_exp_f32_e32 v25, v140
	v_add_f32_e32 v1, v21, v1
	s_waitcnt lgkmcnt(4)
	v_mfma_f32_32x32x16_bf16 v[112:127], v[234:237], v[168:171], v[112:127]
	ds_read_b128 v[234:237], v254 offset:57472
	v_exp_f32_e32 v26, v141
	v_add_f32_e32 v1, v22, v1
	v_exp_f32_e32 v27, v142
	s_waitcnt lgkmcnt(4)
	v_mfma_f32_32x32x16_bf16 v[96:111], v[238:241], v[168:171], v[96:111]
	s_addk_i32 s4, 0x400
	s_mov_b32 s5, m0
	s_mov_b32 m0, s4
	s_nop 0
	global_load_lds_dwordx4 v200, s[56:57]
	s_mov_b32 m0, s5
	v_add_f32_e32 v1, v23, v1
	v_exp_f32_e32 v28, v143
	v_add_f32_e32 v1, v24, v1
	v_add_f32_e32 v1, v25, v1
	s_waitcnt lgkmcnt(3)
	v_mfma_f32_32x32x16_bf16 v[112:127], v[242:245], v[164:167], v[112:127]
	v_add_f32_e32 v1, v26, v1
	v_add_f32_e32 v1, v27, v1
	v_add_f32_e32 v1, v28, v1
	v_add_f32_e32 v205, v205, v1
	v_cvt_pk_bf16_f32 v4, v230, v232
	s_waitcnt lgkmcnt(2)
	v_mfma_f32_32x32x16_bf16 v[96:111], v[246:249], v[164:167], v[96:111]
	v_cvt_pk_bf16_f32 v5, v228, v231
	v_cvt_pk_bf16_f32 v6, v226, v229
	s_nop 1
	v_cvt_pk_bf16_f32 v7, v225, v227
	v_cvt_pk_bf16_f32 v8, v222, v224
	v_cvt_pk_bf16_f32 v9, v220, v223
	s_waitcnt lgkmcnt(1)
	v_mfma_f32_32x32x16_bf16 v[112:127], v[250:253], v[160:163], v[112:127]
	v_cvt_pk_bf16_f32 v10, v218, v221
	v_cvt_pk_bf16_f32 v11, v217, v219
	v_cvt_pk_bf16_f32 v12, v2, v12
	v_cvt_pk_bf16_f32 v13, v13, v14
	v_cvt_pk_bf16_f32 v14, v15, v18
	s_waitcnt lgkmcnt(0)
	v_mfma_f32_32x32x16_bf16 v[96:111], v[234:237], v[160:163], v[96:111]
	v_cvt_pk_bf16_f32 v15, v19, v20
	v_cvt_pk_bf16_f32 v18, v21, v22
	v_cvt_pk_bf16_f32 v19, v23, v24
	v_cvt_pk_bf16_f32 v20, v25, v26
	v_cvt_pk_bf16_f32 v21, v27, v28
	s_setprio 0
	v_add_u32_e32 v2, s74, v206
	ds_read_b64_tr_b16 v[22:23], v2 offset:0
	ds_read_b64_tr_b16 v[24:25], v2 offset:0x800
	ds_read_b64_tr_b16 v[26:27], v2 offset:0x1000
	ds_read_b64_tr_b16 v[28:29], v2 offset:0x1800
	ds_read_b64_tr_b16 v[128:129], v2 offset:0x2000
	ds_read_b64_tr_b16 v[130:131], v2 offset:0x2800
	ds_read_b64_tr_b16 v[132:133], v2 offset:0x3000
	ds_read_b64_tr_b16 v[134:135], v2 offset:0x3800
	s_waitcnt lgkmcnt(6)
	s_nop 0
	v_mfma_f32_32x32x16_bf16 v[32:47], v[4:7], v[22:25], v[32:47]
	ds_read_b64_tr_b16 v[22:23], v2 offset:0x200
	ds_read_b64_tr_b16 v[24:25], v2 offset:0xa00
	s_waitcnt lgkmcnt(6)
	v_mfma_f32_32x32x16_bf16 v[32:47], v[8:11], v[26:29], v[32:47]
	ds_read_b64_tr_b16 v[26:27], v2 offset:0x1200
	ds_read_b64_tr_b16 v[28:29], v2 offset:0x1a00
	s_waitcnt lgkmcnt(6)
	v_mfma_f32_32x32x16_bf16 v[32:47], v[12:15], v[128:131], v[32:47]
	ds_read_b64_tr_b16 v[128:129], v2 offset:0x2200
	ds_read_b64_tr_b16 v[130:131], v2 offset:0x2a00
	s_waitcnt lgkmcnt(6)
	v_mfma_f32_32x32x16_bf16 v[32:47], v[18:21], v[132:135], v[32:47]
	ds_read_b64_tr_b16 v[132:133], v2 offset:0x3200
	ds_read_b64_tr_b16 v[134:135], v2 offset:0x3a00
	s_waitcnt lgkmcnt(6)
	v_mfma_f32_32x32x16_bf16 v[48:63], v[4:7], v[22:25], v[48:63]
	ds_read_b64_tr_b16 v[22:23], v2 offset:0x400
	ds_read_b64_tr_b16 v[24:25], v2 offset:0xc00
	s_waitcnt lgkmcnt(6)
	v_mfma_f32_32x32x16_bf16 v[48:63], v[8:11], v[26:29], v[48:63]
	ds_read_b64_tr_b16 v[26:27], v2 offset:0x1400
	ds_read_b64_tr_b16 v[28:29], v2 offset:0x1c00
	s_waitcnt lgkmcnt(6)
	v_mfma_f32_32x32x16_bf16 v[48:63], v[12:15], v[128:131], v[48:63]
	ds_read_b64_tr_b16 v[128:129], v2 offset:0x2400
	ds_read_b64_tr_b16 v[130:131], v2 offset:0x2c00
	s_waitcnt lgkmcnt(6)
	v_mfma_f32_32x32x16_bf16 v[48:63], v[18:21], v[132:135], v[48:63]
	ds_read_b64_tr_b16 v[132:133], v2 offset:0x3400
	ds_read_b64_tr_b16 v[134:135], v2 offset:0x3c00
	s_waitcnt lgkmcnt(6)
	v_mfma_f32_32x32x16_bf16 v[64:79], v[4:7], v[22:25], v[64:79]
	ds_read_b64_tr_b16 v[22:23], v2 offset:0x600
	ds_read_b64_tr_b16 v[24:25], v2 offset:0xe00
	s_waitcnt lgkmcnt(6)
	v_mfma_f32_32x32x16_bf16 v[64:79], v[8:11], v[26:29], v[64:79]
	ds_read_b64_tr_b16 v[26:27], v2 offset:0x1600
	ds_read_b64_tr_b16 v[28:29], v2 offset:0x1e00
	s_waitcnt lgkmcnt(6)
	v_mfma_f32_32x32x16_bf16 v[64:79], v[12:15], v[128:131], v[64:79]
	ds_read_b64_tr_b16 v[128:129], v2 offset:0x2600
	ds_read_b64_tr_b16 v[130:131], v2 offset:0x2e00
	s_waitcnt lgkmcnt(6)
	v_mfma_f32_32x32x16_bf16 v[64:79], v[18:21], v[132:135], v[64:79]
	ds_read_b64_tr_b16 v[132:133], v2 offset:0x3600
	ds_read_b64_tr_b16 v[134:135], v2 offset:0x3e00
	s_waitcnt lgkmcnt(6)
	v_mfma_f32_32x32x16_bf16 v[80:95], v[4:7], v[22:25], v[80:95]
	v_max_f32_e32 v2, v113, v112
	v_max3_f32 v2, v2, v114, v115
	v_max3_f32 v2, v2, v116, v117
	v_max3_f32 v2, v2, v118, v119
	v_max3_f32 v2, v2, v120, v121
	v_max3_f32 v2, v2, v122, v123
	v_max3_f32 v2, v2, v124, v125
	v_max3_f32 v2, v2, v126, v127
	s_waitcnt lgkmcnt(4)
	v_mfma_f32_32x32x16_bf16 v[80:95], v[8:11], v[26:29], v[80:95]
	v_max3_f32 v2, v2, v96, v97
	v_max3_f32 v2, v2, v98, v99
	v_max3_f32 v2, v2, v100, v101
	v_max3_f32 v2, v2, v102, v103
	v_max3_f32 v2, v2, v104, v105
	v_max3_f32 v2, v2, v106, v107
	v_max3_f32 v2, v2, v108, v109
	v_max3_f32 v2, v2, v110, v111
	s_waitcnt lgkmcnt(2)
	v_mfma_f32_32x32x16_bf16 v[80:95], v[12:15], v[128:131], v[80:95]
	v_mov_b32_e32 v4, v2
	s_nop 1
	v_permlane32_swap_b32_e32 v2, v4
	v_max_f32_e32 v2, v4, v2
	v_sub_f32_e32 v4, v2, v214
	v_cmp_ge_f32_e32 vcc, 0x42b504f3, v4
	v_max_f32_e32 v2, v214, v2
	s_waitcnt lgkmcnt(0)
	v_mfma_f32_32x32x16_bf16 v[80:95], v[18:21], v[132:135], v[80:95]
	s_cmp_eq_u64 vcc, exec
	s_cbranch_scc0 .Lattn0_slowA
	v_mov_b32_e32 v2, v214
.Lattn0_backA:
	s_waitcnt vmcnt(4) lgkmcnt(0)
	s_barrier
	v_add3_u32 v215, s69, v209, v208
	v_add3_u32 v216, s69, v210, v208
	v_add3_u32 v233, s69, v211, v208
	v_add3_u32 v254, s69, v212, v208
	ds_read_b128 v[234:237], v215 offset:49152
	ds_read_b128 v[238:241], v215 offset:57344
	ds_read_b128 v[242:245], v216 offset:49152
	ds_read_b128 v[246:249], v216 offset:57344
	ds_read_b128 v[250:253], v233 offset:49152
	v_mul_f32_e32 v5, 0xbe0293ee, v2
	v_fmamk_f32 v6, v112, 0x3e0293ee, v5
	v_fmamk_f32 v7, v113, 0x3e0293ee, v5
	v_fmamk_f32 v8, v114, 0x3e0293ee, v5
	v_fmamk_f32 v9, v115, 0x3e0293ee, v5
	v_fmamk_f32 v10, v116, 0x3e0293ee, v5
	v_fmamk_f32 v11, v117, 0x3e0293ee, v5
	v_fmamk_f32 v12, v118, 0x3e0293ee, v5
	v_fmamk_f32 v13, v119, 0x3e0293ee, v5
	v_fmamk_f32 v14, v120, 0x3e0293ee, v5
	v_fmamk_f32 v15, v121, 0x3e0293ee, v5
	v_fmamk_f32 v18, v122, 0x3e0293ee, v5
	v_fmamk_f32 v19, v123, 0x3e0293ee, v5
	v_fmamk_f32 v20, v124, 0x3e0293ee, v5
	v_fmamk_f32 v21, v125, 0x3e0293ee, v5
	v_fmamk_f32 v22, v126, 0x3e0293ee, v5
	v_fmamk_f32 v23, v127, 0x3e0293ee, v5
	v_fmamk_f32 v24, v96, 0x3e0293ee, v5
	v_fmamk_f32 v25, v97, 0x3e0293ee, v5
	v_fmamk_f32 v26, v98, 0x3e0293ee, v5
	v_fmamk_f32 v27, v99, 0x3e0293ee, v5
	v_fmamk_f32 v28, v100, 0x3e0293ee, v5
	v_fmamk_f32 v29, v101, 0x3e0293ee, v5
	v_fmamk_f32 v30, v102, 0x3e0293ee, v5
	v_fmamk_f32 v31, v103, 0x3e0293ee, v5
	v_fmamk_f32 v128, v104, 0x3e0293ee, v5
	v_fmamk_f32 v129, v105, 0x3e0293ee, v5
	v_fmamk_f32 v130, v106, 0x3e0293ee, v5
	v_fmamk_f32 v131, v107, 0x3e0293ee, v5
	v_fmamk_f32 v132, v108, 0x3e0293ee, v5
	v_fmamk_f32 v133, v109, 0x3e0293ee, v5
	v_fmamk_f32 v134, v110, 0x3e0293ee, v5
	v_fmac_f32_e32 v5, 0x3e0293ee, v111
	s_setprio 1
	s_waitcnt lgkmcnt(4)
	v_mfma_f32_32x32x16_bf16 v[112:127], v[234:237], v[188:191], 0
	ds_read_b128 v[234:237], v233 offset:57344
	v_exp_f32_e32 v135, v6
	v_exp_f32_e32 v136, v7
	v_exp_f32_e32 v137, v8
	v_exp_f32_e32 v138, v9
	s_waitcnt lgkmcnt(4)
	v_mfma_f32_32x32x16_bf16 v[96:111], v[238:241], v[188:191], 0
	ds_read_b128 v[238:241], v254 offset:49152
	v_exp_f32_e32 v10, v10
	v_exp_f32_e32 v11, v11
	v_exp_f32_e32 v12, v12
	s_waitcnt lgkmcnt(4)
	v_mfma_f32_32x32x16_bf16 v[112:127], v[242:245], v[184:187], v[112:127]
	ds_read_b128 v[242:245], v254 offset:57344
	s_add_i32 s4, s77, s42
	s_mov_b32 s5, m0
	s_mov_b32 m0, s4
	s_nop 0
	global_load_lds_dwordx4 v197, s[70:71]
	s_mov_b32 m0, s5
	v_exp_f32_e32 v13, v13
	v_exp_f32_e32 v14, v14
	v_exp_f32_e32 v15, v15
	v_exp_f32_e32 v18, v18
	s_waitcnt lgkmcnt(4)
	v_mfma_f32_32x32x16_bf16 v[96:111], v[246:249], v[184:187], v[96:111]
	ds_read_b128 v[246:249], v215 offset:49280
	v_exp_f32_e32 v19, v19
	v_exp_f32_e32 v20, v20
	v_exp_f32_e32 v21, v21
	s_waitcnt lgkmcnt(4)
	v_mfma_f32_32x32x16_bf16 v[112:127], v[250:253], v[180:183], v[112:127]
	ds_read_b128 v[250:253], v215 offset:57472
	v_exp_f32_e32 v22, v22
	v_exp_f32_e32 v23, v23
	v_exp_f32_e32 v7, v24
	v_exp_f32_e32 v24, v25
	s_waitcnt lgkmcnt(4)
	v_mfma_f32_32x32x16_bf16 v[96:111], v[234:237], v[180:183], v[96:111]
	ds_read_b128 v[234:237], v216 offset:49280
	s_addk_i32 s4, 0x400
	s_mov_b32 s5, m0
	s_mov_b32 m0, s4
	s_nop 0
	global_load_lds_dwordx4 v198, s[70:71]
	s_mov_b32 m0, s5
	v_exp_f32_e32 v25, v26
	v_exp_f32_e32 v26, v27
	v_exp_f32_e32 v27, v28
	s_waitcnt lgkmcnt(4)
	v_mfma_f32_32x32x16_bf16 v[112:127], v[238:241], v[176:179], v[112:127]
	ds_read_b128 v[238:241], v216 offset:57472
	v_exp_f32_e32 v28, v29
	v_exp_f32_e32 v29, v30
	v_exp_f32_e32 v30, v31
	v_exp_f32_e32 v31, v128
	s_waitcnt lgkmcnt(4)
	v_mfma_f32_32x32x16_bf16 v[96:111], v[242:245], v[176:179], v[96:111]
	ds_read_b128 v[242:245], v233 offset:49280
	v_exp_f32_e32 v128, v129
	v_exp_f32_e32 v129, v130
	v_exp_f32_e32 v130, v131
	s_waitcnt lgkmcnt(4)
	v_mfma_f32_32x32x16_bf16 v[112:127], v[246:249], v[172:175], v[112:127]
	ds_read_b128 v[246:249], v233 offset:57472
	s_add_u32 s4, s56, 0x4000
	s_addc_u32 s5, s57, 0
	s_add_i32 s72, s74, s97
	s_mov_b32 s73, m0
	s_mov_b32 m0, s72
	s_nop 0
	global_load_lds_dwordx4 v199, s[4:5]
	s_mov_b32 m0, s73
	v_exp_f32_e32 v131, v132
	v_exp_f32_e32 v132, v133
	v_exp_f32_e32 v133, v134
	v_exp_f32_e32 v134, v5
	s_waitcnt lgkmcnt(4)
	v_mfma_f32_32x32x16_bf16 v[96:111], v[250:253], v[172:175], v[96:111]
	ds_read_b128 v[250:253], v254 offset:49280
	v_add_f32_e32 v5, 0, v135
	v_add_f32_e32 v5, v136, v5
	v_add_f32_e32 v5, v137, v5
	v_add_f32_e32 v5, v138, v5
	v_add_f32_e32 v5, v10, v5
	v_add_f32_e32 v5, v11, v5
	v_add_f32_e32 v5, v12, v5
	s_waitcnt lgkmcnt(4)
	v_mfma_f32_32x32x16_bf16 v[112:127], v[234:237], v[168:171], v[112:127]
	ds_read_b128 v[234:237], v254 offset:57472
	v_add_f32_e32 v5, v13, v5
	v_add_f32_e32 v5, v14, v5
	v_add_f32_e32 v5, v15, v5
	v_add_f32_e32 v5, v18, v5
	v_add_f32_e32 v5, v19, v5
	v_add_f32_e32 v5, v20, v5
	v_add_f32_e32 v5, v21, v5
	s_waitcnt lgkmcnt(4)
	v_mfma_f32_32x32x16_bf16 v[96:111], v[238:241], v[168:171], v[96:111]
	s_addk_i32 s72, 0x400
	s_mov_b32 s73, m0
	s_mov_b32 m0, s72
	s_nop 0
	global_load_lds_dwordx4 v200, s[4:5]
	s_mov_b32 m0, s73
	v_add_f32_e32 v5, v22, v5
	v_add_f32_e32 v5, v23, v5
	v_add_f32_e32 v5, v7, v5
	v_add_f32_e32 v5, v24, v5
	v_add_f32_e32 v5, v25, v5
	v_add_f32_e32 v5, v26, v5
	v_add_f32_e32 v5, v27, v5
	s_waitcnt lgkmcnt(3)
	v_mfma_f32_32x32x16_bf16 v[112:127], v[242:245], v[164:167], v[112:127]
	v_add_f32_e32 v5, v28, v5
	v_add_f32_e32 v5, v29, v5
	v_add_f32_e32 v5, v30, v5
	v_add_f32_e32 v5, v31, v5
	v_add_f32_e32 v5, v128, v5
	v_add_f32_e32 v5, v129, v5
	v_add_f32_e32 v5, v130, v5
	s_waitcnt lgkmcnt(2)
	v_mfma_f32_32x32x16_bf16 v[96:111], v[246:249], v[164:167], v[96:111]
	v_add_f32_e32 v5, v131, v5
	v_add_f32_e32 v5, v132, v5
	v_add_f32_e32 v5, v133, v5
	v_add_f32_e32 v5, v134, v5
	v_add_f32_e32 v205, v205, v5
	v_cvt_pk_bf16_f32 v8, v135, v136
	v_cvt_pk_bf16_f32 v9, v137, v138
	s_waitcnt lgkmcnt(1)
	v_mfma_f32_32x32x16_bf16 v[112:127], v[250:253], v[160:163], v[112:127]
	v_cvt_pk_bf16_f32 v10, v10, v11
	s_nop 1
	v_cvt_pk_bf16_f32 v11, v12, v13
	v_cvt_pk_bf16_f32 v12, v14, v15
	v_cvt_pk_bf16_f32 v13, v18, v19
	v_cvt_pk_bf16_f32 v14, v20, v21
	v_cvt_pk_bf16_f32 v15, v22, v23
	v_cvt_pk_bf16_f32 v18, v7, v24
	s_waitcnt lgkmcnt(0)
	v_mfma_f32_32x32x16_bf16 v[96:111], v[234:237], v[160:163], v[96:111]
	v_cvt_pk_bf16_f32 v19, v25, v26
	v_cvt_pk_bf16_f32 v20, v27, v28
	v_cvt_pk_bf16_f32 v21, v29, v30
	v_cvt_pk_bf16_f32 v22, v31, v128
	v_cvt_pk_bf16_f32 v23, v129, v130
	v_cvt_pk_bf16_f32 v24, v131, v132
	v_cvt_pk_bf16_f32 v25, v133, v134
	s_setprio 0
	v_add_u32_e32 v7, s77, v206
	ds_read_b64_tr_b16 v[26:27], v7 offset:0
	ds_read_b64_tr_b16 v[28:29], v7 offset:0x800
	ds_read_b64_tr_b16 v[128:129], v7 offset:0x1000
	ds_read_b64_tr_b16 v[130:131], v7 offset:0x1800
	ds_read_b64_tr_b16 v[132:133], v7 offset:0x2000
	ds_read_b64_tr_b16 v[134:135], v7 offset:0x2800
	ds_read_b64_tr_b16 v[136:137], v7 offset:0x3000
	ds_read_b64_tr_b16 v[138:139], v7 offset:0x3800
	s_waitcnt lgkmcnt(6)
	s_nop 0
	v_mfma_f32_32x32x16_bf16 v[32:47], v[8:11], v[26:29], v[32:47]
	ds_read_b64_tr_b16 v[26:27], v7 offset:0x200
	ds_read_b64_tr_b16 v[28:29], v7 offset:0xa00
	s_waitcnt lgkmcnt(6)
	v_mfma_f32_32x32x16_bf16 v[32:47], v[12:15], v[128:131], v[32:47]
	ds_read_b64_tr_b16 v[128:129], v7 offset:0x1200
	ds_read_b64_tr_b16 v[130:131], v7 offset:0x1a00
	s_waitcnt lgkmcnt(6)
	v_mfma_f32_32x32x16_bf16 v[32:47], v[18:21], v[132:135], v[32:47]
	ds_read_b64_tr_b16 v[132:133], v7 offset:0x2200
	ds_read_b64_tr_b16 v[134:135], v7 offset:0x2a00
	s_waitcnt lgkmcnt(6)
	v_mfma_f32_32x32x16_bf16 v[32:47], v[22:25], v[136:139], v[32:47]
	ds_read_b64_tr_b16 v[136:137], v7 offset:0x3200
	ds_read_b64_tr_b16 v[138:139], v7 offset:0x3a00
	s_waitcnt lgkmcnt(6)
	v_mfma_f32_32x32x16_bf16 v[48:63], v[8:11], v[26:29], v[48:63]
	ds_read_b64_tr_b16 v[26:27], v7 offset:0x400
	ds_read_b64_tr_b16 v[28:29], v7 offset:0xc00
	s_waitcnt lgkmcnt(6)
	v_mfma_f32_32x32x16_bf16 v[48:63], v[12:15], v[128:131], v[48:63]
	ds_read_b64_tr_b16 v[128:129], v7 offset:0x1400
	ds_read_b64_tr_b16 v[130:131], v7 offset:0x1c00
	s_waitcnt lgkmcnt(6)
	v_mfma_f32_32x32x16_bf16 v[48:63], v[18:21], v[132:135], v[48:63]
	ds_read_b64_tr_b16 v[132:133], v7 offset:0x2400
	ds_read_b64_tr_b16 v[134:135], v7 offset:0x2c00
	s_waitcnt lgkmcnt(6)
	v_mfma_f32_32x32x16_bf16 v[48:63], v[22:25], v[136:139], v[48:63]
	ds_read_b64_tr_b16 v[136:137], v7 offset:0x3400
	ds_read_b64_tr_b16 v[138:139], v7 offset:0x3c00
	s_waitcnt lgkmcnt(6)
	v_mfma_f32_32x32x16_bf16 v[64:79], v[8:11], v[26:29], v[64:79]
	ds_read_b64_tr_b16 v[26:27], v7 offset:0x600
	ds_read_b64_tr_b16 v[28:29], v7 offset:0xe00
	s_waitcnt lgkmcnt(6)
	v_mfma_f32_32x32x16_bf16 v[64:79], v[12:15], v[128:131], v[64:79]
	ds_read_b64_tr_b16 v[128:129], v7 offset:0x1600
	ds_read_b64_tr_b16 v[130:131], v7 offset:0x1e00
	s_waitcnt lgkmcnt(6)
	v_mfma_f32_32x32x16_bf16 v[64:79], v[18:21], v[132:135], v[64:79]
	ds_read_b64_tr_b16 v[132:133], v7 offset:0x2600
	ds_read_b64_tr_b16 v[134:135], v7 offset:0x2e00
	s_waitcnt lgkmcnt(6)
	v_mfma_f32_32x32x16_bf16 v[64:79], v[22:25], v[136:139], v[64:79]
	ds_read_b64_tr_b16 v[136:137], v7 offset:0x3600
	ds_read_b64_tr_b16 v[138:139], v7 offset:0x3e00
	s_waitcnt lgkmcnt(6)
	v_mfma_f32_32x32x16_bf16 v[80:95], v[8:11], v[26:29], v[80:95]
	v_max_f32_e32 v7, v113, v112
	v_max3_f32 v7, v7, v114, v115
	v_max3_f32 v7, v7, v116, v117
	v_max3_f32 v7, v7, v118, v119
	v_max3_f32 v7, v7, v120, v121
	v_max3_f32 v7, v7, v122, v123
	v_max3_f32 v7, v7, v124, v125
	v_max3_f32 v7, v7, v126, v127
	s_waitcnt lgkmcnt(4)
	v_mfma_f32_32x32x16_bf16 v[80:95], v[12:15], v[128:131], v[80:95]
	v_max3_f32 v7, v7, v96, v97
	v_max3_f32 v7, v7, v98, v99
	v_max3_f32 v7, v7, v100, v101
	v_max3_f32 v7, v7, v102, v103
	v_max3_f32 v7, v7, v104, v105
	v_max3_f32 v7, v7, v106, v107
	v_max3_f32 v7, v7, v108, v109
	v_max3_f32 v7, v7, v110, v111
	s_waitcnt lgkmcnt(2)
	v_mfma_f32_32x32x16_bf16 v[80:95], v[18:21], v[132:135], v[80:95]
	v_mov_b32_e32 v8, v7
	s_nop 1
	v_permlane32_swap_b32_e32 v7, v8
	v_max_f32_e32 v7, v8, v7
	v_sub_f32_e32 v8, v7, v2
	v_cmp_ge_f32_e32 vcc, 0x42b504f3, v8
	v_max_f32_e32 v8, v2, v7
	s_waitcnt lgkmcnt(0)
	v_mfma_f32_32x32x16_bf16 v[80:95], v[22:25], v[136:139], v[80:95]
	s_cmp_eq_u64 vcc, exec
	s_cbranch_scc0 .Lattn0_slowB
	v_mov_b32_e32 v214, v2
.Lattn0_backB:
	v_mul_f32_e32 v2, 0xbe0293ee, v214
	v_fmamk_f32 v8, v112, 0x3e0293ee, v2
	v_fmamk_f32 v9, v113, 0x3e0293ee, v2
	v_fmamk_f32 v10, v114, 0x3e0293ee, v2
	v_fmamk_f32 v11, v115, 0x3e0293ee, v2
	v_fmamk_f32 v12, v116, 0x3e0293ee, v2
	v_fmamk_f32 v13, v117, 0x3e0293ee, v2
	v_fmamk_f32 v14, v118, 0x3e0293ee, v2
	v_fmamk_f32 v15, v119, 0x3e0293ee, v2
	v_fmamk_f32 v18, v120, 0x3e0293ee, v2
	v_fmamk_f32 v19, v121, 0x3e0293ee, v2
	v_fmamk_f32 v20, v122, 0x3e0293ee, v2
	v_fmamk_f32 v21, v123, 0x3e0293ee, v2
	v_fmamk_f32 v22, v124, 0x3e0293ee, v2
	v_fmamk_f32 v23, v125, 0x3e0293ee, v2
	v_fmamk_f32 v24, v126, 0x3e0293ee, v2
	v_fmamk_f32 v25, v127, 0x3e0293ee, v2
	s_add_u32 s56, s56, 0x8000
	v_exp_f32_e32 v230, v8
	v_exp_f32_e32 v232, v9
	v_exp_f32_e32 v228, v10
	v_exp_f32_e32 v231, v11
	v_exp_f32_e32 v226, v12
	v_exp_f32_e32 v229, v13
	v_exp_f32_e32 v225, v14
	v_exp_f32_e32 v227, v15
	v_exp_f32_e32 v222, v18
	v_exp_f32_e32 v224, v19
	v_exp_f32_e32 v220, v20
	v_exp_f32_e32 v223, v21
	v_exp_f32_e32 v218, v22
	v_exp_f32_e32 v221, v23
	v_exp_f32_e32 v217, v24
	v_exp_f32_e32 v219, v25
	s_addc_u32 s57, s57, 0
	s_add_i32 s4, s45, 2
	s_add_u32 s70, s70, 0x8000
	s_waitcnt vmcnt(4) lgkmcnt(0)
	s_barrier
	s_addc_u32 s71, s71, 0
	v_pk_fma_f32 v[142:143], v[110:111], s[12:13], v[2:3] op_sel_hi:[1,0,0]
	v_pk_fma_f32 v[140:141], v[108:109], s[12:13], v[2:3] op_sel_hi:[1,0,0]
	v_pk_fma_f32 v[138:139], v[106:107], s[12:13], v[2:3] op_sel_hi:[1,0,0]
	v_pk_fma_f32 v[136:137], v[104:105], s[12:13], v[2:3] op_sel_hi:[1,0,0]
	v_pk_fma_f32 v[134:135], v[102:103], s[12:13], v[2:3] op_sel_hi:[1,0,0]
	v_pk_fma_f32 v[132:133], v[100:101], s[12:13], v[2:3] op_sel_hi:[1,0,0]
	v_pk_fma_f32 v[130:131], v[98:99], s[12:13], v[2:3] op_sel_hi:[1,0,0]
	v_pk_fma_f32 v[128:129], v[96:97], s[12:13], v[2:3] op_sel_hi:[1,0,0]
	s_cmp_ge_i32 s4, s21
	s_cbranch_scc1 .LBB0_321
	s_mov_b32 s45, s4
	s_mov_b32 s72, s69
	s_mov_b32 s69, s77
	s_branch .LBB0_309
.Lattn0_slowA:
	v_sub_f32_e32 v4, v214, v2
	v_mul_f32_e32 v4, 0x3e0293ee, v4
	v_exp_f32_e32 v4, v4
	s_nop 0
	v_mul_f32_e32 v205, v4, v205
	v_cmp_gt_f32_e32 vcc, 1.0, v4
	s_cbranch_vccz .Lattn0_backA
	s_and_saveexec_b64 s[72:73], s[2:3]
	ds_write_b32 v204, v4 offset:128
	s_or_b64 exec, exec, s[72:73]
	s_waitcnt lgkmcnt(0)
	ds_read_b128 v[6:9], v203 offset:224
	ds_read_b128 v[10:13], v203 offset:192
	ds_read_b128 v[18:21], v203 offset:160
	ds_read_b128 v[22:25], v203 offset:128
	s_waitcnt lgkmcnt(3)
	v_pk_mul_f32 v[46:47], v[46:47], v[8:9]
	s_waitcnt lgkmcnt(2)
	v_pk_mul_f32 v[42:43], v[42:43], v[12:13]
	s_waitcnt lgkmcnt(1)
	v_pk_mul_f32 v[38:39], v[38:39], v[20:21]
	s_waitcnt lgkmcnt(0)
	v_pk_mul_f32 v[34:35], v[34:35], v[24:25]
	v_pk_mul_f32 v[44:45], v[44:45], v[6:7]
	v_pk_mul_f32 v[40:41], v[40:41], v[10:11]
	v_pk_mul_f32 v[36:37], v[36:37], v[18:19]
	v_pk_mul_f32 v[32:33], v[32:33], v[22:23]
	v_pk_mul_f32 v[62:63], v[62:63], v[8:9]
	v_pk_mul_f32 v[58:59], v[58:59], v[12:13]
	v_pk_mul_f32 v[54:55], v[54:55], v[20:21]
	v_pk_mul_f32 v[50:51], v[50:51], v[24:25]
	v_pk_mul_f32 v[60:61], v[60:61], v[6:7]
	v_pk_mul_f32 v[56:57], v[56:57], v[10:11]
	v_pk_mul_f32 v[52:53], v[52:53], v[18:19]
	v_pk_mul_f32 v[48:49], v[48:49], v[22:23]
	v_pk_mul_f32 v[78:79], v[78:79], v[8:9]
	v_pk_mul_f32 v[74:75], v[74:75], v[12:13]
	v_pk_mul_f32 v[70:71], v[70:71], v[20:21]
	v_pk_mul_f32 v[66:67], v[66:67], v[24:25]
	v_pk_mul_f32 v[76:77], v[76:77], v[6:7]
	v_pk_mul_f32 v[72:73], v[72:73], v[10:11]
	v_pk_mul_f32 v[68:69], v[68:69], v[18:19]
	v_pk_mul_f32 v[64:65], v[64:65], v[22:23]
	v_pk_mul_f32 v[94:95], v[94:95], v[8:9]
	v_pk_mul_f32 v[90:91], v[90:91], v[12:13]
	v_pk_mul_f32 v[86:87], v[86:87], v[20:21]
	v_pk_mul_f32 v[82:83], v[82:83], v[24:25]
	v_pk_mul_f32 v[92:93], v[92:93], v[6:7]
	v_pk_mul_f32 v[88:89], v[88:89], v[10:11]
	v_pk_mul_f32 v[84:85], v[84:85], v[18:19]
	v_pk_mul_f32 v[80:81], v[80:81], v[22:23]
	s_branch .Lattn0_backA
.Lattn0_slowB:
	v_sub_f32_e32 v7, v2, v8
	v_mul_f32_e32 v7, 0x3e0293ee, v7
	v_exp_f32_e32 v7, v7
	v_mov_b32_e32 v214, v8
	v_mul_f32_e32 v205, v7, v205
	v_cmp_gt_f32_e32 vcc, 1.0, v7
	s_cbranch_vccz .Lattn0_backB
	s_and_saveexec_b64 s[72:73], s[2:3]
	ds_write_b32 v204, v7 offset:128
	s_or_b64 exec, exec, s[72:73]
	s_waitcnt lgkmcnt(0)
	ds_read_b128 v[10:13], v203 offset:224
	ds_read_b128 v[18:21], v203 offset:192
	ds_read_b128 v[22:25], v203 offset:160
	ds_read_b128 v[26:29], v203 offset:128
	s_waitcnt lgkmcnt(3)
	v_pk_mul_f32 v[46:47], v[46:47], v[12:13]
	s_waitcnt lgkmcnt(2)
	v_pk_mul_f32 v[42:43], v[42:43], v[20:21]
	s_waitcnt lgkmcnt(1)
	v_pk_mul_f32 v[38:39], v[38:39], v[24:25]
	s_waitcnt lgkmcnt(0)
	v_pk_mul_f32 v[34:35], v[34:35], v[28:29]
	v_pk_mul_f32 v[44:45], v[44:45], v[10:11]
	v_pk_mul_f32 v[40:41], v[40:41], v[18:19]
	v_pk_mul_f32 v[36:37], v[36:37], v[22:23]
	v_pk_mul_f32 v[32:33], v[32:33], v[26:27]
	v_pk_mul_f32 v[62:63], v[62:63], v[12:13]
	v_pk_mul_f32 v[58:59], v[58:59], v[20:21]
	v_pk_mul_f32 v[54:55], v[54:55], v[24:25]
	v_pk_mul_f32 v[50:51], v[50:51], v[28:29]
	v_pk_mul_f32 v[60:61], v[60:61], v[10:11]
	v_pk_mul_f32 v[56:57], v[56:57], v[18:19]
	v_pk_mul_f32 v[52:53], v[52:53], v[22:23]
	v_pk_mul_f32 v[48:49], v[48:49], v[26:27]
	v_pk_mul_f32 v[78:79], v[78:79], v[12:13]
	v_pk_mul_f32 v[74:75], v[74:75], v[20:21]
	v_pk_mul_f32 v[70:71], v[70:71], v[24:25]
	v_pk_mul_f32 v[66:67], v[66:67], v[28:29]
	v_pk_mul_f32 v[76:77], v[76:77], v[10:11]
	v_pk_mul_f32 v[72:73], v[72:73], v[18:19]
	v_pk_mul_f32 v[68:69], v[68:69], v[22:23]
	v_pk_mul_f32 v[64:65], v[64:65], v[26:27]
	v_pk_mul_f32 v[94:95], v[94:95], v[12:13]
	v_pk_mul_f32 v[90:91], v[90:91], v[20:21]
	v_pk_mul_f32 v[86:87], v[86:87], v[24:25]
	v_pk_mul_f32 v[82:83], v[82:83], v[28:29]
	v_pk_mul_f32 v[92:93], v[92:93], v[10:11]
	v_pk_mul_f32 v[88:89], v[88:89], v[18:19]
	v_pk_mul_f32 v[84:85], v[84:85], v[22:23]
	v_pk_mul_f32 v[80:81], v[80:81], v[26:27]
	s_branch .Lattn0_backB

.LBB0_321:
	s_add_i32 s56, s45, 1
	s_mov_b32 s72, s69
	s_mov_b32 s87, s74
	s_mov_b32 s69, s77
	v_mov_b32_e32 v213, 1.0
	v_mov_b32_e32 v215, v205
	s_nop 1
	v_permlane32_swap_b32_e32 v205, v215
	v_add_f32_e32 v205, v205, v215
	s_add_i32 s44, s44, 4
	s_add_i32 s2, s56, 1
	s_cmp_ge_i32 s2, s44
	s_cbranch_scc1 .LBB0_320
